# speedup vs baseline: 1.0249x; 1.0003x over previous
; template <int MODE> ...
;     ...
;                 float sacc = 0.f;
; #pragma unroll
;                 for (int r = 0; r < 16; ++r) { p0[r] = ex2(p0[r] - mhat); p1[r] = ex2(p1[r] - mhat); sacc += p0[r] + p1[r]; }
;                 lsum += sacc;
;             } else {
;                 f32x16 L0, L1;
; #pragma unroll
;                 for (int r = 0; r < 16; ++r) {
;                     const float s0 = p0[r], s1 = p1[r];
;                     float l0 = lg2(1.0f + ex2(s0)), l1 = lg2(1.0f + ex2(s1));
;                     l0 = s0 > 32.f ? s0 : l0; l1 = s1 > 32.f ? s1 : l1;
;                     float g0 = s0 - l0, g1 = s1 - l1;
;                     if (!full) { const int k0 = crow(r, hi_m), k1 = k0 + 32; if (!(k0 < dq)) { l0 = 0.f; g0 = -INFINITY; } if (!(k1 < dq)) { l1 = 0.f; g1 = -INFINITY; } }
;                     L0[r] = l0; L1[r] = l1; p0[r] = g0; p1[r] = g1;
;                 }
;                 float T[8], U[8], Tp[8];
; #pragma unroll
;                 for (int g = 0; g < 8; ++g) { const int b = 4 * (g & 3);
;                     const float a0 = g < 4 ? L0[b] : L1[b], a1 = g < 4 ? L0[b + 1] : L1[b + 1], a2 = g < 4 ? L0[b + 2] : L1[b + 2], a3 = g < 4 ? L0[b + 3] : L1[b + 3];
;                     const float s2 = a3 + a2, s1 = s2 + a1; T[g] = s1 + a0;
;                     if (g < 4) { L0[b] = s1; L0[b + 1] = s2; L0[b + 2] = a3; L0[b + 3] = 0.f; } else { L1[b] = s1; L1[b + 1] = s2; L1[b + 2] = a3; L1[b + 3] = 0.f; }
;                     auto rr = __builtin_amdgcn_permlane32_swap(__float_as_uint(T[g]), __float_as_uint(T[g]), false, false);
;                     const float x0 = __uint_as_float(rr[0]), x1 = __uint_as_float(rr[1]);
;                     U[g] = x0 + x1; Tp[g] = hi == 0 ? x1 : 0.f; }
;                 float ss = 0.f;
; #pragma unroll
;                 for (int g = 7; g >= 0; --g) { const int b = 4 * (g & 3); const float base = Rp + ss + Tp[g];
; #pragma unroll
;                     for (int e = 0; e < 4; ++e) { if (g < 4) p0[b + e] = ex2(p0[b + e] - base - L0[b + e]); else p1[b + e] = ex2(p1[b + e] - base - L1[b + e]); }
;                     ss += U[g]; }
;                 Rp += ss;
;             }
;             pw0 = (u32x4){cvtpk(p0[0], p0[1]), cvtpk(p0[2], p0[3]), cvtpk(p0[4], p0[5]), cvtpk(p0[6], p0[7])};
;             pw1 = (u32x4){cvtpk(p0[8], p0[9]), cvtpk(p0[10], p0[11]), cvtpk(p0[12], p0[13]), cvtpk(p0[14], p0[15])};
.LBB0_241:
	v_sub_f32_e32 v0, v96, v184
	v_sub_f32_e32 v4, v83, v184
	v_exp_f32_e32 v3, v0
	v_sub_f32_e32 v0, v80, v184
	v_exp_f32_e32 v10, v4
	v_sub_f32_e32 v4, v100, v184
	v_sub_f32_e32 v8, v85, v184
	v_sub_f32_e32 v80, v89, v184
	v_exp_f32_e32 v9, v4
	v_sub_f32_e32 v4, v84, v184
	v_exp_f32_e32 v14, v8
	v_sub_f32_e32 v8, v102, v184
	v_exp_f32_e32 v102, v80
	v_sub_f32_e32 v80, v106, v184
	v_exp_f32_e32 v15, v4
	v_sub_f32_e32 v4, v101, v184
	v_exp_f32_e32 v101, v80
	v_sub_f32_e32 v80, v90, v184
	v_sub_f32_e32 v2, v81, v184
	v_sub_f32_e32 v12, v87, v184
	v_exp_f32_e32 v185, v80
	v_sub_f32_e32 v80, v107, v184
	v_exp_f32_e32 v6, v2
	v_sub_f32_e32 v2, v98, v184
	v_exp_f32_e32 v98, v12
	v_sub_f32_e32 v12, v104, v184
	v_exp_f32_e32 v96, v80
	v_sub_f32_e32 v80, v91, v184
	v_exp_f32_e32 v7, v0
	v_sub_f32_e32 v0, v97, v184
	v_exp_f32_e32 v5, v2
	v_sub_f32_e32 v2, v82, v184
	v_exp_f32_e32 v13, v8
	v_sub_f32_e32 v8, v86, v184
	v_exp_f32_e32 v97, v12
	v_sub_f32_e32 v12, v88, v184
	v_exp_f32_e32 v106, v80
	v_sub_f32_e32 v80, v108, v184
	v_exp_f32_e32 v11, v2
	v_sub_f32_e32 v2, v99, v184
	v_exp_f32_e32 v99, v8
	v_sub_f32_e32 v8, v103, v184
	v_exp_f32_e32 v103, v12
	v_sub_f32_e32 v12, v105, v184
	v_exp_f32_e32 v105, v80
	v_sub_f32_e32 v80, v92, v184
	v_exp_f32_e32 v187, v80
	v_sub_f32_e32 v80, v109, v184
	v_exp_f32_e32 v100, v80
	v_sub_f32_e32 v80, v93, v184
	v_exp_f32_e32 v108, v80
	v_sub_f32_e32 v80, v110, v184
	v_exp_f32_e32 v186, v80
	v_sub_f32_e32 v80, v94, v184
	v_exp_f32_e32 v188, v80
	v_sub_f32_e32 v80, v111, v184
	v_exp_f32_e32 v104, v80
	v_sub_f32_e32 v80, v95, v184
	v_exp_f32_e32 v0, v0
	v_exp_f32_e32 v2, v2
	v_exp_f32_e32 v4, v4
	v_exp_f32_e32 v8, v8
	v_exp_f32_e32 v12, v12
	v_exp_f32_e32 v110, v80
	s_mul_hi_u32 s14, s24, 0xaaaaaaab
	s_lshr_b32 s14, s14, 1
	v_cvt_pk_bf16_f32 v80, v3, v0
	v_cvt_pk_bf16_f32 v81, v5, v2
	v_cvt_pk_bf16_f32 v82, v9, v4
	v_cvt_pk_bf16_f32 v83, v13, v8
	v_cvt_pk_bf16_f32 v88, v97, v12
	v_cvt_pk_bf16_f32 v89, v101, v96
	v_cvt_pk_bf16_f32 v90, v105, v100
	v_cvt_pk_bf16_f32 v91, v186, v104
	v_cvt_pk_bf16_f32 v84, v7, v6
	v_cvt_pk_bf16_f32 v85, v11, v10
	v_cvt_pk_bf16_f32 v86, v15, v14
	v_cvt_pk_bf16_f32 v87, v99, v98
	v_cvt_pk_bf16_f32 v92, v103, v102
	v_cvt_pk_bf16_f32 v93, v185, v106
	v_cvt_pk_bf16_f32 v94, v187, v108
	s_andn2_b64 vcc, exec, s[6:7]
	v_cvt_pk_bf16_f32 v95, v188, v110
	s_cbranch_vccnz .LBB0_243
	s_mul_i32 s14, s14, 0xffff4000
	v_add_u32_e32 v189, s14, v182
	v_add3_u32 v189, v189, v147, s23
	ds_read_b64_tr_b16 v[190:191], v189
	ds_read_b64_tr_b16 v[192:193], v189 offset:512
	ds_read_b64_tr_b16 v[196:197], v189 offset:1024
	ds_read_b64_tr_b16 v[198:199], v189 offset:1536
	ds_read_b64_tr_b16 v[202:203], v189 offset:2048
	ds_read_b64_tr_b16 v[204:205], v189 offset:2560
	ds_read_b64_tr_b16 v[216:217], v189 offset:3072
	ds_read_b64_tr_b16 v[218:219], v189 offset:3584
	ds_read_b64_tr_b16 v[220:221], v189 offset:4096
	ds_read_b64_tr_b16 v[222:223], v189 offset:4608
	ds_read_b64_tr_b16 v[224:225], v189 offset:5120
	ds_read_b64_tr_b16 v[226:227], v189 offset:5632
	ds_read_b64_tr_b16 v[228:229], v189 offset:6144
	ds_read_b64_tr_b16 v[230:231], v189 offset:6656
	ds_read_b64_tr_b16 v[232:233], v189 offset:7168
	ds_read_b64_tr_b16 v[234:235], v189 offset:7680
	ds_read_b64_tr_b16 v[236:237], v189 offset:8192
	ds_read_b64_tr_b16 v[238:239], v189 offset:8704
	ds_read_b64_tr_b16 v[240:241], v189 offset:9216
	ds_read_b64_tr_b16 v[242:243], v189 offset:9728
	ds_read_b64_tr_b16 v[244:245], v189 offset:10240
	ds_read_b64_tr_b16 v[246:247], v189 offset:10752
	ds_read_b64_tr_b16 v[248:249], v189 offset:11264
	ds_read_b64_tr_b16 v[250:251], v189 offset:11776
	ds_read_b64_tr_b16 v[206:207], v189 offset:12288
	ds_read_b64_tr_b16 v[208:209], v189 offset:12800
	ds_read_b64_tr_b16 v[158:159], v189 offset:13312
	ds_read_b64_tr_b16 v[160:161], v189 offset:13824
	ds_read_b64_tr_b16 v[138:139], v189 offset:14336
	ds_read_b64_tr_b16 v[140:141], v189 offset:14848
	ds_read_b64_tr_b16 v[148:149], v189 offset:15360
	ds_read_b64_tr_b16 v[150:151], v189 offset:15872
	s_waitcnt lgkmcnt(14)
	v_mfma_f32_32x32x16_bf16 v[64:79], v[80:83], v[190:193], v[64:79]
	v_mfma_f32_32x32x16_bf16 v[48:63], v[80:83], v[220:223], v[48:63]
	v_mfma_f32_32x32x16_bf16 v[64:79], v[88:91], v[196:199], v[64:79]
	v_mfma_f32_32x32x16_bf16 v[48:63], v[88:91], v[224:227], v[48:63]
	v_mfma_f32_32x32x16_bf16 v[64:79], v[84:87], v[202:205], v[64:79]
	v_mfma_f32_32x32x16_bf16 v[48:63], v[84:87], v[228:231], v[48:63]
	v_mfma_f32_32x32x16_bf16 v[64:79], v[92:95], v[216:219], v[64:79]
	v_mfma_f32_32x32x16_bf16 v[48:63], v[92:95], v[232:235], v[48:63]
	v_mfma_f32_32x32x16_bf16 v[32:47], v[80:83], v[236:239], v[32:47]
	s_waitcnt lgkmcnt(6)
	v_mfma_f32_32x32x16_bf16 v[16:31], v[80:83], v[206:209], v[16:31]
	v_mfma_f32_32x32x16_bf16 v[32:47], v[88:91], v[240:243], v[32:47]
	s_waitcnt lgkmcnt(4)
	v_mfma_f32_32x32x16_bf16 v[16:31], v[88:91], v[158:161], v[16:31]
	v_mfma_f32_32x32x16_bf16 v[32:47], v[84:87], v[244:247], v[32:47]
	s_waitcnt lgkmcnt(2)
	v_mfma_f32_32x32x16_bf16 v[16:31], v[84:87], v[138:141], v[16:31]
	v_mfma_f32_32x32x16_bf16 v[32:47], v[92:95], v[248:251], v[32:47]
	s_waitcnt lgkmcnt(0)
	v_mfma_f32_32x32x16_bf16 v[16:31], v[92:95], v[148:151], v[16:31]
	s_branch .LBB0_244
